# weight-copy items in phases 6/9/11 remapped off the blocks that own an extra GEMM tile (item = wave id - 256/128), so the copies run in otherwise idle blocks
# speedup vs baseline: 1.0203x; 1.0203x over previous
; #define LAS __attribute__((address_space(3)))
; #define KIN(i) (((const float* const __attribute__((address_space(4)))*)kp)[i])
; DEV void tr_matrix(const float* W, int ldw, int K, int Ndst, bf16_t* WT, int map, int nvalid, int src_off, LAS float* scr, int gw, int NGW, int lane) {
;     const int nblk = Ndst / 32, nit = (K / 64) * nblk;
;     for (int it = gw; it < nit; it += NGW) { const int kb = it / nblk, nb = it % nblk, d0 = nb * 32; int s0 = d0;
;         if (map == 1) { const int pn = d0 >> 8, wi = d0 & 255, bj = wi >> 7, jj = wi & 127; s0 = bj * DFF + 128 * pn + jj; }
;         else if (map == 2) { if (d0 < 1024) s0 = (d0 >> 6) * 128 + (d0 & 63); else { const int n2 = d0 - 1024; s0 = (n2 >> 6) * 128 + 64 + (n2 & 63); } }
;         else if (map == 3) { if (d0 >= nvalid) s0 = -1; }
;         tr_item(W, ldw, K, WT, d0, s0 < 0 ? -1 : s0 + src_off, kb * 64, scr, lane); }
; template <int LO, int HI>
; DEV void run_phases(LAS unsigned char* lds, const int ph_lo, const int ph_hi, const int G, const int wave0, unsigned& nbar) {
;     ...
;             tr_matrix(KIN(I_MIN), 416, 1024, 512, BF(W_MLAIN), 3, 416, 0, scr, gw, NGW, lane);
;             tr_matrix(KIN(I_MUQ), 1536, 256, 1536, BF(W_WUQ), 0, 0, 0, scr, gw, NGW, lane);
;             tr_matrix(KIN(I_MUKV), 2048, 128, 2048, BF(W_WUKV), 2, 0, 0, scr, gw, NGW, lane);
;             tr_matrix(KIN(I_MWO), 1024, 1024, 1024, BF(W_WO), 0, 0, 0, scr, gw, NGW, lane);
.LBB0_676:
	s_and_b64 vcc, exec, s[2:3]
	s_cbranch_vccz .LBB0_764
	v_readlane_b32 s2, v249, 35
	s_lshl_b32 s10, s2, 14
	s_add_i32 s11, s10, 0
	v_readlane_b32 s2, v249, 38
	s_sub_i32 s2, s2, 0x100
	s_cmpk_gt_u32 s2, 0xff
	v_readlane_b32 s3, v249, 39
	s_cbranch_scc1 .LBB0_698
	v_readlane_b32 s2, v250, 23
	v_readlane_b32 s3, v250, 24
	s_load_dwordx2 s[2:3], s[2:3], 0xc8
	v_lshlrev_b32_e32 v0, 2, v130
	v_and_b32_e32 v0, 0x7c, v0
	s_waitcnt vmcnt(1)
	v_lshlrev_b32_e32 v4, 3, v140
	s_waitcnt vmcnt(0)
	v_lshrrev_b32_e32 v9, 3, v140
	s_waitcnt lgkmcnt(0)
	v_lshl_add_u64 v[2:3], s[2:3], 0, v[0:1]
	v_and_b32_e32 v4, 56, v4
	v_readlane_b32 s2, v250, 44
	v_mul_u32_u24_e32 v6, 0x84, v4
	v_lshlrev_b32_e32 v4, 1, v4
	v_mov_b32_e32 v5, v1
	v_readlane_b32 s3, v250, 45
	v_lshlrev_b32_e32 v7, 2, v9
	v_lshrrev_b32_e32 v8, 5, v140
	v_lshl_add_u64 v[4:5], s[2:3], 0, v[4:5]
	v_add3_u32 v10, s11, v6, v7
	v_mov_b32_e32 v6, s10
	s_movk_i32 s2, 0x84
	v_mad_u32_u24 v6, v8, s2, v6
	v_readlane_b32 s2, v249, 38
	s_sub_i32 s2, s2, 0x100
	v_or_b32_e32 v11, 8, v9
	v_or_b32_e32 v12, 16, v9
	v_or_b32_e32 v13, 24, v9
	v_add3_u32 v0, v6, v0, 0
	s_mov_b32 s12, s2
	v_readlane_b32 s3, v249, 39
	s_branch .LBB0_680

; #define KIN(i) (((const float* const __attribute__((address_space(4)))*)kp)[i])
; template <int LO, int HI>
; DEV void run_phases(LAS unsigned char* lds, const int ph_lo, const int ph_hi, const int G, const int wave0, unsigned& nbar) {
;     ...
;             tr_matrix(KIN(I_MIN), 416, 1024, 512, BF(W_MLAIN), 3, 416, 0, scr, gw, NGW, lane);
;             tr_matrix(KIN(I_MUQ), 1536, 256, 1536, BF(W_WUQ), 0, 0, 0, scr, gw, NGW, lane);
;             tr_matrix(KIN(I_MUKV), 2048, 128, 2048, BF(W_WUKV), 2, 0, 0, scr, gw, NGW, lane);
;             tr_matrix(KIN(I_MWO), 1024, 1024, 1024, BF(W_WO), 0, 0, 0, scr, gw, NGW, lane);
.LBB0_698:
	v_readlane_b32 s8, v249, 38
	s_sub_i32 s8, s8, 0x100
	s_cmpk_gt_u32 s8, 0xbf
	v_readlane_b32 s9, v249, 39
	s_cbranch_scc0 .LBB0_701
	s_cmpk_gt_u32 s8, 0x7f
	s_cbranch_scc0 .LBB0_722
.LBB0_700:
	s_cmpk_gt_u32 s8, 0x1ff
	s_cbranch_scc0 .LBB0_743
	s_branch .LBB0_763

; #define KIN(i) (((const float* const __attribute__((address_space(4)))*)kp)[i])
; template <int LO, int HI>
; DEV void run_phases(LAS unsigned char* lds, const int ph_lo, const int ph_hi, const int G, const int wave0, unsigned& nbar) {
;     ...
;             tr_matrix(KIN(I_MIN), 416, 1024, 512, BF(W_MLAIN), 3, 416, 0, scr, gw, NGW, lane);
;             tr_matrix(KIN(I_MUQ), 1536, 256, 1536, BF(W_WUQ), 0, 0, 0, scr, gw, NGW, lane);
;             tr_matrix(KIN(I_MUKV), 2048, 128, 2048, BF(W_WUKV), 2, 0, 0, scr, gw, NGW, lane);
;             tr_matrix(KIN(I_MWO), 1024, 1024, 1024, BF(W_WO), 0, 0, 0, scr, gw, NGW, lane);
.LBB0_721:
	v_readlane_b32 s8, v249, 38
	s_sub_i32 s8, s8, 0x100
	v_readlane_b32 s9, v249, 39
	s_cmpk_gt_u32 s8, 0x7f
	s_cbranch_scc1 .LBB0_700

; #define LAS __attribute__((address_space(3)))
; #define KIN(i) (((const float* const __attribute__((address_space(4)))*)kp)[i])
; DEV void tr_matrix(const float* W, int ldw, int K, int Ndst, bf16_t* WT, int map, int nvalid, int src_off, LAS float* scr, int gw, int NGW, int lane) {
;     const int nblk = Ndst / 32, nit = (K / 64) * nblk;
;     for (int it = gw; it < nit; it += NGW) { const int kb = it / nblk, nb = it % nblk, d0 = nb * 32; int s0 = d0;
;         if (map == 1) { const int pn = d0 >> 8, wi = d0 & 255, bj = wi >> 7, jj = wi & 127; s0 = bj * DFF + 128 * pn + jj; }
;         else if (map == 2) { if (d0 < 1024) s0 = (d0 >> 6) * 128 + (d0 & 63); else { const int n2 = d0 - 1024; s0 = (n2 >> 6) * 128 + 64 + (n2 & 63); } }
;         else if (map == 3) { if (d0 >= nvalid) s0 = -1; }
;         tr_item(W, ldw, K, WT, d0, s0 < 0 ? -1 : s0 + src_off, kb * 64, scr, lane); }
; template <int LO, int HI>
; DEV void run_phases(LAS unsigned char* lds, const int ph_lo, const int ph_hi, const int G, const int wave0, unsigned& nbar) {
;     ...
;             tr_matrix(KIN(I_MIN), 416, 1024, 512, BF(W_MLAIN), 3, 416, 0, scr, gw, NGW, lane);
;             tr_matrix(KIN(I_MUQ), 1536, 256, 1536, BF(W_WUQ), 0, 0, 0, scr, gw, NGW, lane);
;             tr_matrix(KIN(I_MUKV), 2048, 128, 2048, BF(W_WUKV), 2, 0, 0, scr, gw, NGW, lane);
;             tr_matrix(KIN(I_MWO), 1024, 1024, 1024, BF(W_WO), 0, 0, 0, scr, gw, NGW, lane);
.LBB0_742:
	v_readlane_b32 s8, v249, 38
	s_sub_i32 s8, s8, 0x100
	v_readlane_b32 s9, v249, 39
	s_cmpk_gt_u32 s8, 0x1ff
	s_cbranch_scc1 .LBB0_763
.LBB0_743:
	v_readlane_b32 s4, v250, 23
	v_readlane_b32 s5, v250, 24
	s_load_dwordx2 s[2:3], s[4:5], 0x100
	v_lshlrev_b32_e32 v0, 2, v130
	v_and_b32_e32 v0, 0x7c, v0
	s_waitcnt vmcnt(1)
	v_lshlrev_b32_e32 v4, 3, v140
	v_and_b32_e32 v4, 56, v4
	s_waitcnt lgkmcnt(0)
	v_lshl_add_u64 v[2:3], s[2:3], 0, v[0:1]
	s_load_dwordx2 s[2:3], s[4:5], 0x110
	s_waitcnt vmcnt(0)
	v_lshrrev_b32_e32 v9, 3, v140
	v_mul_u32_u24_e32 v6, 0x84, v4
	v_lshlrev_b32_e32 v4, 1, v4
	v_mov_b32_e32 v5, v1
	s_waitcnt lgkmcnt(0)
	v_lshl_add_u64 v[4:5], s[2:3], 0, v[4:5]
	s_mov_b64 s[2:3], 0x700000
	v_lshlrev_b32_e32 v7, 2, v9
	v_lshrrev_b32_e32 v8, 5, v140
	v_lshl_add_u64 v[4:5], v[4:5], 0, s[2:3]
	v_add3_u32 v10, s11, v6, v7
	v_mov_b32_e32 v6, s10
	s_movk_i32 s2, 0x84
	v_mad_u32_u24 v6, v8, s2, v6
	v_readlane_b32 s2, v249, 38
	s_sub_i32 s2, s2, 0x100
	v_or_b32_e32 v11, 8, v9
	v_or_b32_e32 v12, 16, v9
	v_or_b32_e32 v13, 24, v9
	v_add3_u32 v0, v6, v0, 0
	s_mov_b32 s10, s2
	v_readlane_b32 s3, v249, 39
	s_branch .LBB0_745

; #define LAS __attribute__((address_space(3)))
; DEV unsigned cvt_pk_bf16(float lo, float hi) { unsigned r; asm volatile("v_cvt_pk_bf16_f32 %0, %1, %2" : "=v"(r) : "v"(lo), "v"(hi)); return r; }
; #define KIN(i) (((const float* const __attribute__((address_space(4)))*)kp)[i])
; DEV void tr_item(const float* W, int ldw, int K, bf16_t* WT, int dst_n0, int src_n0, int k0, LAS float* scr, int lane) {
; #pragma unroll 8
;     for (int i = 0; i < 32; ++i) { const int kk = 2 * i + (lane >> 5); scr[kk * 33 + (lane & 31)] = (src_n0 >= 0) ? W[(size_t)(k0 + kk) * ldw + src_n0 + (lane & 31)] : 0.f; }
;     asm volatile("s_waitcnt lgkmcnt(0)" ::: "memory");
;     const int c = lane & 7;
; #pragma unroll
;     for (int j = 0; j < 4; ++j) { const int n = (lane >> 3) + 8 * j; const LAS float* s = scr + (8 * c) * 33 + n;
;         u32x4 o; o.x = cvt_pk_bf16(s[0 * 33], s[1 * 33]); o.y = cvt_pk_bf16(s[2 * 33], s[3 * 33]); o.z = cvt_pk_bf16(s[4 * 33], s[5 * 33]); o.w = cvt_pk_bf16(s[6 * 33], s[7 * 33]);
;         *(u32x4*)(WT + (size_t)(dst_n0 + n) * K + k0 + 8 * c) = o; }
;     asm volatile("s_waitcnt lgkmcnt(0)" ::: "memory");
; }
; DEV void tr_matrix(const float* W, int ldw, int K, int Ndst, bf16_t* WT, int map, int nvalid, int src_off, LAS float* scr, int gw, int NGW, int lane) {
;     const int nblk = Ndst / 32, nit = (K / 64) * nblk;
;     for (int it = gw; it < nit; it += NGW) { const int kb = it / nblk, nb = it % nblk, d0 = nb * 32; int s0 = d0;
;         if (map == 1) { const int pn = d0 >> 8, wi = d0 & 255, bj = wi >> 7, jj = wi & 127; s0 = bj * DFF + 128 * pn + jj; }
;         else if (map == 2) { if (d0 < 1024) s0 = (d0 >> 6) * 128 + (d0 & 63); else { const int n2 = d0 - 1024; s0 = (n2 >> 6) * 128 + 64 + (n2 & 63); } }
;         else if (map == 3) { if (d0 >= nvalid) s0 = -1; }
;         tr_item(W, ldw, K, WT, d0, s0 < 0 ? -1 : s0 + src_off, kb * 64, scr, lane); }
; template <int LO, int HI>
; DEV void run_phases(LAS unsigned char* lds, const int ph_lo, const int ph_hi, const int G, const int wave0, unsigned& nbar) {
;     ...
;             tr_matrix(KIN(I_FUP) + (size_t)1024 * 2 * DFF, 2 * DFF, 1024, 2 * DFF, BF(W_WUP), 1, 0, 0, scr, gw, NGW, lane);
.LBB0_1316:
	s_and_b64 vcc, exec, s[6:7]
	s_cbranch_vccz .LBB0_1339
	v_readlane_b32 s0, v250, 27
	v_readlane_b32 s1, v250, 28
	s_and_b64 vcc, exec, s[0:1]
	v_readlane_b32 s14, v249, 38
	v_readlane_b32 s15, v249, 39
	s_cbranch_vccz .LBB0_1341
	s_sub_i32 s8, s14, 0x100
	s_cmpk_gt_u32 s8, 0xaff
	s_cbranch_scc1 .LBB0_1340
	v_readlane_b32 s0, v250, 23
	v_lshlrev_b32_e32 v0, 3, v140
	v_readlane_b32 s1, v250, 24
	v_readlane_b32 s2, v249, 35
	v_and_b32_e32 v0, 56, v0
	v_readlane_b32 s4, v250, 32
	s_load_dwordx2 s[0:1], s[0:1], 0x40
	s_lshl_b32 s2, s2, 14
	v_lshrrev_b32_e32 v23, 3, v140
	s_waitcnt vmcnt(1)
	v_mul_u32_u24_e32 v4, 0x84, v0
	v_lshlrev_b32_e32 v0, 1, v0
	v_readlane_b32 s5, v250, 33
	s_add_i32 s3, s2, 0
	v_lshrrev_b32_e32 v22, 5, v140
	v_lshl_add_u64 v[2:3], s[4:5], 0, v[0:1]
	v_lshlrev_b32_e32 v0, 2, v23
	v_add3_u32 v24, s3, v4, v0
	v_mul_u32_u24_e32 v0, 0x84, v22
	v_or_b32_e32 v4, s2, v0
	v_lshlrev_b32_e32 v0, 2, v130
	v_and_b32_e32 v0, 0x7c, v0
	v_add3_u32 v28, v4, v0, 0
	s_waitcnt lgkmcnt(0)
	v_lshl_add_u64 v[4:5], s[0:1], 0, v[0:1]
	s_mov_b64 s[0:1], 0x1600000
	v_lshl_add_u64 v[4:5], v[4:5], 0, s[0:1]
	v_readlane_b32 s0, v249, 38
	v_or_b32_e32 v25, 8, v23
	v_or_b32_e32 v26, 16, v23
	v_or_b32_e32 v27, 24, v23
	v_or_b32_e32 v0, 14, v22
	v_or_b32_e32 v29, 12, v22
	v_or_b32_e32 v30, 10, v22
	v_or_b32_e32 v31, 8, v22
	v_or_b32_e32 v32, 6, v22
	v_or_b32_e32 v33, 4, v22
	v_or_b32_e32 v34, 2, v22
	s_sub_i32 s8, s0, 0x100
	v_readlane_b32 s1, v249, 39
	s_branch .LBB0_1321
.LBB0_1320:
	s_waitcnt lgkmcnt(0)
	ds_read2_b32 v[8:9], v24 offset1:33
	s_waitcnt lgkmcnt(0)
	v_cvt_pk_bf16_f32 v8, v8, v9
	ds_read2_b32 v[10:11], v24 offset0:66 offset1:99
	s_waitcnt lgkmcnt(0)
	v_cvt_pk_bf16_f32 v9, v10, v11
	ds_read2_b32 v[10:11], v24 offset0:132 offset1:165
	s_waitcnt lgkmcnt(0)
	v_cvt_pk_bf16_f32 v10, v10, v11
	ds_read2_b32 v[12:13], v24 offset0:198 offset1:231
	s_waitcnt lgkmcnt(0)
	v_cvt_pk_bf16_f32 v11, v12, v13
	v_or_b32_e32 v12, s9, v23
	s_ashr_i32 s1, s0, 31
	v_ashrrev_i32_e32 v13, 31, v12
	v_lshl_add_u64 v[6:7], s[0:1], 1, v[2:3]
	v_lshlrev_b64 v[12:13], 11, v[12:13]
	v_lshl_add_u64 v[12:13], v[6:7], 0, v[12:13]
	global_store_dwordx4 v[12:13], v[8:11], off
	ds_read2_b32 v[8:9], v24 offset0:8 offset1:41
	s_movk_i32 s0, 0x700
	s_waitcnt lgkmcnt(0)
	v_cvt_pk_bf16_f32 v8, v8, v9
	ds_read2_b32 v[10:11], v24 offset0:74 offset1:107
	s_waitcnt lgkmcnt(0)
	v_cvt_pk_bf16_f32 v9, v10, v11
	ds_read2_b32 v[10:11], v24 offset0:140 offset1:173
	s_waitcnt lgkmcnt(0)
	v_cvt_pk_bf16_f32 v10, v10, v11
	ds_read2_b32 v[12:13], v24 offset0:206 offset1:239
	s_waitcnt lgkmcnt(0)
	v_cvt_pk_bf16_f32 v11, v12, v13
	v_or_b32_e32 v12, s9, v25
	v_ashrrev_i32_e32 v13, 31, v12
	v_lshlrev_b64 v[12:13], 11, v[12:13]
	v_lshl_add_u64 v[12:13], v[6:7], 0, v[12:13]
	global_store_dwordx4 v[12:13], v[8:11], off
	ds_read2_b32 v[8:9], v24 offset0:16 offset1:49
	s_add_i32 s8, s8, s0
	s_waitcnt lgkmcnt(0)
	v_cvt_pk_bf16_f32 v8, v8, v9
	ds_read2_b32 v[10:11], v24 offset0:82 offset1:115
	s_waitcnt lgkmcnt(0)
	v_cvt_pk_bf16_f32 v9, v10, v11
	ds_read2_b32 v[10:11], v24 offset0:148 offset1:181
	s_waitcnt lgkmcnt(0)
	v_cvt_pk_bf16_f32 v10, v10, v11
	ds_read2_b32 v[12:13], v24 offset0:214 offset1:247
	s_waitcnt lgkmcnt(0)
	v_cvt_pk_bf16_f32 v11, v12, v13
	v_or_b32_e32 v12, s9, v26
	v_ashrrev_i32_e32 v13, 31, v12
	v_lshlrev_b64 v[12:13], 11, v[12:13]
	v_lshl_add_u64 v[12:13], v[6:7], 0, v[12:13]
	global_store_dwordx4 v[12:13], v[8:11], off
	ds_read2_b32 v[8:9], v24 offset0:24 offset1:57
	s_cmpk_lt_i32 s8, 0xb00
	s_waitcnt lgkmcnt(0)
	v_cvt_pk_bf16_f32 v8, v8, v9
	ds_read2_b32 v[10:11], v24 offset0:90 offset1:123
	s_waitcnt lgkmcnt(0)
	v_cvt_pk_bf16_f32 v9, v10, v11
	ds_read2_b32 v[10:11], v24 offset0:156 offset1:189
	s_waitcnt lgkmcnt(0)
	v_cvt_pk_bf16_f32 v10, v10, v11
	ds_read2_b32 v[12:13], v24 offset0:222 offset1:255
	s_waitcnt lgkmcnt(0)
	v_cvt_pk_bf16_f32 v11, v12, v13
	v_or_b32_e32 v12, s9, v27
	v_ashrrev_i32_e32 v13, 31, v12
	v_lshlrev_b64 v[12:13], 11, v[12:13]
	v_lshl_add_u64 v[6:7], v[6:7], 0, v[12:13]
	global_store_dwordx4 v[6:7], v[8:11], off
	s_waitcnt lgkmcnt(0)
	s_cbranch_scc0 .LBB0_1340

; #define LAS __attribute__((address_space(3)))
; #define KIN(i) (((const float* const __attribute__((address_space(4)))*)kp)[i])
; DEV void tr_matrix(const float* W, int ldw, int K, int Ndst, bf16_t* WT, int map, int nvalid, int src_off, LAS float* scr, int gw, int NGW, int lane) {
;     const int nblk = Ndst / 32, nit = (K / 64) * nblk;
;     for (int it = gw; it < nit; it += NGW) { const int kb = it / nblk, nb = it % nblk, d0 = nb * 32; int s0 = d0;
;         if (map == 1) { const int pn = d0 >> 8, wi = d0 & 255, bj = wi >> 7, jj = wi & 127; s0 = bj * DFF + 128 * pn + jj; }
;         else if (map == 2) { if (d0 < 1024) s0 = (d0 >> 6) * 128 + (d0 & 63); else { const int n2 = d0 - 1024; s0 = (n2 >> 6) * 128 + 64 + (n2 & 63); } }
;         else if (map == 3) { if (d0 >= nvalid) s0 = -1; }
;         tr_item(W, ldw, K, WT, d0, s0 < 0 ? -1 : s0 + src_off, kb * 64, scr, lane); }
; template <int LO, int HI>
; DEV void run_phases(LAS unsigned char* lds, const int ph_lo, const int ph_hi, const int G, const int wave0, unsigned& nbar) {
;     ...
;             tr_matrix(KIN(I_FDOWN) + (size_t)DFF * 1024, 1024, DFF, 1024, BF(W_WDOWN), 0, 0, 0, scr, gw, NGW, lane);
.LBB0_2156:
	s_andn2_b64 vcc, exec, s[2:3]
	s_cbranch_vccnz .LBB0_2200
	s_cmp_lt_i32 s82, 11
	s_mov_b64 s[2:3], -1
	s_cbranch_scc1 .LBB0_2182
	s_cmp_eq_u32 s82, 11
	s_cbranch_scc0 .LBB0_2181
	s_sub_i32 s1, s0, 0x80
	s_cmpk_gt_u32 s1, 0x57f
	s_cbranch_scc1 .LBB0_2180
	v_readlane_b32 s2, v251, 31
	v_readlane_b32 s3, v251, 32
	s_load_dwordx2 s[2:3], s[2:3], 0x58
	v_lshlrev_b32_e32 v0, 2, v131
	v_lshlrev_b32_e32 v2, 3, v133
	s_lshl_b32 s1, s28, 14
	v_and_b32_e32 v96, 0x7c, v0
	s_waitcnt vmcnt(1)
	v_lshrrev_b32_e32 v7, 3, v133
	v_and_b32_e32 v2, 56, v2
	s_add_i32 s4, s1, 0
	v_lshrrev_b32_e32 v6, 5, v133
	s_waitcnt lgkmcnt(0)
	v_lshl_add_u64 v[0:1], s[2:3], 0, v[96:97]
	s_mov_b64 s[2:3], 0xb00000
	v_mul_u32_u24_e32 v4, 0x84, v2
	v_lshlrev_b32_e32 v5, 2, v7
	v_lshl_add_u64 v[0:1], v[0:1], 0, s[2:3]
	v_readlane_b32 s2, v248, 18
	s_waitcnt vmcnt(0)
	v_add3_u32 v8, s4, v4, v5
	v_mul_u32_u24_e32 v4, 0x84, v6
	v_lshlrev_b32_e32 v2, 1, v2
	v_mov_b32_e32 v3, v97
	v_readlane_b32 s3, v248, 19
	v_or_b32_e32 v4, s1, v4
	v_or_b32_e32 v9, 8, v7
	v_lshl_add_u64 v[2:3], s[2:3], 0, v[2:3]
	v_or_b32_e32 v10, 16, v7
	v_or_b32_e32 v11, 24, v7
	v_add3_u32 v12, v4, v96, 0
	s_sub_i32 s1, s0, 0x80
	s_branch .LBB0_2162
